# plus: P6 scan chunk-carry loops issue their 4 summary loads together (counted vmcnt) instead of one load per round trip
# baseline (speedup 1.0000x reference)
; __global__ void __launch_bounds__(NWAVES * 64, 2) fwd(Args args) {
;     ...
;                 float hf0 = 0.f, hf1 = 0.f, hr0 = 0.f, hr1 = 0.f;
; #pragma unroll 4
;                 for (int cc = c_lo; cc < c; ++cc) { const f32x4 s = *(const f32x4*)(SUM + ((size_t)(cc * 2 + 0) * D + ch)); hf0 = s.x * hf0 + s.y; hf1 = s.z * hf1 + s.w; }
.LBB0_543:
	v_ashrrev_i32_e32 v19, 31, v18
	v_lshlrev_b64 v[36:37], 15, v[18:19]
	v_lshl_add_u64 v[36:37], v[20:21], 0, v[36:37]
	global_load_dwordx4 v[36:39], v[36:37], off
	v_add_u32_e32 v48, 2, v18
	v_ashrrev_i32_e32 v49, 31, v48
	v_lshlrev_b64 v[48:49], 15, v[48:49]
	v_lshl_add_u64 v[48:49], v[20:21], 0, v[48:49]
	global_load_dwordx4 v[48:51], v[48:49], off
	v_add_u32_e32 v52, 4, v18
	v_ashrrev_i32_e32 v53, 31, v52
	v_lshlrev_b64 v[52:53], 15, v[52:53]
	v_lshl_add_u64 v[52:53], v[20:21], 0, v[52:53]
	global_load_dwordx4 v[52:55], v[52:53], off
	v_add_u32_e32 v56, 6, v18
	v_ashrrev_i32_e32 v57, 31, v56
	v_lshlrev_b64 v[56:57], 15, v[56:57]
	v_lshl_add_u64 v[56:57], v[20:21], 0, v[56:57]
	global_load_dwordx4 v[56:59], v[56:57], off
	v_add_u32_e32 v2, 4, v2
	v_cmp_ge_i32_e32 vcc, v2, v26
	s_or_b64 s[38:39], vcc, s[38:39]
	v_add_u32_e32 v18, 8, v18
	s_waitcnt vmcnt(3)
	v_mov_b32_e32 v40, v36
	v_mov_b32_e32 v41, v38
	v_mov_b32_e32 v38, v37
	v_pk_fma_f32 v[24:25], v[24:25], v[40:41], v[38:39]
	s_waitcnt vmcnt(2)
	v_mov_b32_e32 v40, v48
	v_mov_b32_e32 v41, v50
	v_mov_b32_e32 v50, v49
	v_pk_fma_f32 v[24:25], v[24:25], v[40:41], v[50:51]
	s_waitcnt vmcnt(1)
	v_mov_b32_e32 v40, v52
	v_mov_b32_e32 v41, v54
	v_mov_b32_e32 v54, v53
	v_pk_fma_f32 v[24:25], v[24:25], v[40:41], v[54:55]
	s_waitcnt vmcnt(0)
	v_mov_b32_e32 v40, v56
	v_mov_b32_e32 v41, v58
	v_mov_b32_e32 v58, v57
	v_pk_fma_f32 v[24:25], v[24:25], v[40:41], v[58:59]
	s_andn2_b64 exec, exec, s[38:39]
	s_cbranch_execnz .LBB0_543
	s_or_b64 exec, exec, s[38:39]

; __global__ void __launch_bounds__(NWAVES * 64, 2) fwd(Args args) {
;     ...
; #pragma unroll 4
.LBB0_553:
	v_add_u32_e32 v36, 6, v22
	v_ashrrev_i32_e32 v37, 31, v36
	v_lshlrev_b64 v[36:37], 15, v[36:37]
	v_lshl_add_u64 v[36:37], v[20:21], 0, v[36:37]
	global_load_dwordx4 v[36:39], v[36:37], off
	v_add_u32_e32 v48, 4, v22
	v_ashrrev_i32_e32 v49, 31, v48
	v_lshlrev_b64 v[48:49], 15, v[48:49]
	v_lshl_add_u64 v[48:49], v[20:21], 0, v[48:49]
	global_load_dwordx4 v[48:51], v[48:49], off
	v_add_u32_e32 v52, 2, v22
	v_ashrrev_i32_e32 v53, 31, v52
	v_lshlrev_b64 v[52:53], 15, v[52:53]
	v_lshl_add_u64 v[52:53], v[20:21], 0, v[52:53]
	global_load_dwordx4 v[52:55], v[52:53], off
	v_ashrrev_i32_e32 v23, 31, v22
	v_lshlrev_b64 v[56:57], 15, v[22:23]
	v_lshl_add_u64 v[56:57], v[20:21], 0, v[56:57]
	global_load_dwordx4 v[56:59], v[56:57], off
	v_add_u32_e32 v28, -4, v28
	v_cmp_le_i32_e32 vcc, v28, v26
	s_or_b64 s[38:39], vcc, s[38:39]
	v_add_u32_e32 v22, -8, v22
	s_waitcnt vmcnt(3)
	v_mov_b32_e32 v40, v36
	v_mov_b32_e32 v41, v38
	v_mov_b32_e32 v38, v37
	v_pk_fma_f32 v[18:19], v[18:19], v[40:41], v[38:39]
	s_waitcnt vmcnt(2)
	v_mov_b32_e32 v40, v48
	v_mov_b32_e32 v41, v50
	v_mov_b32_e32 v50, v49
	v_pk_fma_f32 v[18:19], v[18:19], v[40:41], v[50:51]
	s_waitcnt vmcnt(1)
	v_mov_b32_e32 v40, v52
	v_mov_b32_e32 v41, v54
	v_mov_b32_e32 v54, v53
	v_pk_fma_f32 v[18:19], v[18:19], v[40:41], v[54:55]
	s_waitcnt vmcnt(0)
	v_mov_b32_e32 v40, v56
	v_mov_b32_e32 v41, v58
	v_mov_b32_e32 v58, v57
	v_pk_fma_f32 v[18:19], v[18:19], v[40:41], v[58:59]
	s_andn2_b64 exec, exec, s[38:39]
	s_cbranch_execnz .LBB0_553
	s_or_b64 exec, exec, s[38:39]
